# v39 + short-conv phase: row prefetch issued before the history-row wait (two memory latencies overlapped)
# speedup vs baseline: 1.0028x; 1.0028x over previous
; __device__ __forceinline__ float bf_lo(unsigned u) { return __uint_as_float(u << 16); }
; __device__ __forceinline__ float bf_hi(unsigned u) { return __uint_as_float(u & 0xffff0000u); }
; __device__ __forceinline__ void conv_phase(const bf16_t* proj, bf16_t* ycat, const float* cw, const float* cb, int tid) {
;     ...
;     for (int chunk = (blockIdx.x * NTHR + tid) >> 6; chunk < M / 16; chunk += (gridDim.x * NTHR) >> 6) {
;         const int row0 = chunk * 16, t0 = row0 & (SEQ - 1);
;         float p1[8], p2[8];
; #pragma unroll
;         for (int e = 0; e < 8; ++e) { p1[e] = 0.f; p2[e] = 0.f; }
;         if (t0 >= 2) {
;             const bf16_t* p = proj + (size_t)(row0 - 2) * 1024 + 512 + c0;
;             const u32x4 pa = *(const u32x4*)p, pb = *(const u32x4*)(p + 1024);
; #pragma unroll
;             for (int e = 0; e < 4; ++e) { p2[2 * e] = bf_lo(pa[e]); p2[2 * e + 1] = bf_hi(pa[e]); p1[2 * e] = bf_lo(pb[e]); p1[2 * e + 1] = bf_hi(pb[e]); }
;         }
; #pragma unroll 4
;         for (int rr = 0; rr < 16; ++rr) {
;             const bf16_t* p = proj + (size_t)(row0 + rr) * 1024 + c0;
;             const u32x4 gb = *(const u32x4*)p, pc = *(const u32x4*)(p + 512);
.LBB0_285:
	v_and_b32_e32 v32, 0x1ff, v68
	v_cmp_ne_u32_e32 vcc, 0, v32
	v_mov_b32_e32 v34, 0
	v_mov_b32_e32 v35, 0
	v_mov_b32_e32 v62, 0
	v_mov_b32_e32 v63, 0
	s_waitcnt vmcnt(12)
	v_mov_b32_e32 v64, 0
	v_mov_b32_e32 v65, 0
	v_mov_b32_e32 v66, 0
	v_mov_b32_e32 v67, 0
	v_mov_b32_e32 v48, 0
	v_mov_b32_e32 v49, 0
	v_mov_b32_e32 v50, 0
	v_mov_b32_e32 v51, 0
	v_mov_b32_e32 v32, 0
	v_mov_b32_e32 v33, 0
	v_mov_b32_e32 v52, 0
	v_mov_b32_e32 v53, 0
	v_mov_b32_e32 v75, 0
	v_mov_b32_e32 v74, v69
	v_lshl_add_u64 v[166:167], v[74:75], 1, v[36:37]
	global_load_dwordx4 v[76:79], v[166:167], off
	global_load_dwordx4 v[80:83], v[166:167], off offset:1024
	v_add_u32_e32 v74, 0x400, v69
	v_lshl_add_u64 v[166:167], v[74:75], 1, v[36:37]
	global_load_dwordx4 v[84:87], v[166:167], off
	global_load_dwordx4 v[88:91], v[166:167], off offset:1024
	v_add_u32_e32 v74, 0x800, v69
	v_lshl_add_u64 v[166:167], v[74:75], 1, v[36:37]
	global_load_dwordx4 v[92:95], v[166:167], off
	global_load_dwordx4 v[96:99], v[166:167], off offset:1024
	v_add_u32_e32 v74, 0xc00, v69
	v_lshl_add_u64 v[166:167], v[74:75], 1, v[36:37]
	global_load_dwordx4 v[100:103], v[166:167], off
	global_load_dwordx4 v[104:107], v[166:167], off offset:1024
	v_add_u32_e32 v74, 0x1000, v69
	v_lshl_add_u64 v[166:167], v[74:75], 1, v[36:37]
	global_load_dwordx4 v[108:111], v[166:167], off
	global_load_dwordx4 v[112:115], v[166:167], off offset:1024
	v_add_u32_e32 v74, 0x1400, v69
	v_lshl_add_u64 v[166:167], v[74:75], 1, v[36:37]
	global_load_dwordx4 v[116:119], v[166:167], off
	global_load_dwordx4 v[120:123], v[166:167], off offset:1024
	v_add_u32_e32 v74, 0x1800, v69
	v_lshl_add_u64 v[166:167], v[74:75], 1, v[36:37]
	global_load_dwordx4 v[124:127], v[166:167], off
	global_load_dwordx4 v[128:131], v[166:167], off offset:1024
	v_add_u32_e32 v74, 0x1c00, v69
	v_lshl_add_u64 v[166:167], v[74:75], 1, v[36:37]
	global_load_dwordx4 v[132:135], v[166:167], off
	global_load_dwordx4 v[138:141], v[166:167], off offset:1024
	v_add_u32_e32 v74, 0x2000, v69
	v_lshl_add_u64 v[166:167], v[74:75], 1, v[36:37]
	global_load_dwordx4 v[142:145], v[166:167], off
	global_load_dwordx4 v[146:149], v[166:167], off offset:1024
	v_add_u32_e32 v74, 0x2400, v69
	v_lshl_add_u64 v[166:167], v[74:75], 1, v[36:37]
	global_load_dwordx4 v[150:153], v[166:167], off
	global_load_dwordx4 v[154:157], v[166:167], off offset:1024
	v_add_u32_e32 v74, 0x2800, v69
	v_lshl_add_u64 v[166:167], v[74:75], 1, v[36:37]
	global_load_dwordx4 v[158:161], v[166:167], off
	global_load_dwordx4 v[162:165], v[166:167], off offset:1024
	v_add_u32_e32 v74, 0x2c00, v69
	v_lshl_add_u64 v[166:167], v[74:75], 1, v[36:37]
	global_load_dwordx4 v[186:189], v[166:167], off
	global_load_dwordx4 v[190:193], v[166:167], off offset:1024
	v_add_u32_e32 v74, 0x3000, v69
	v_lshl_add_u64 v[166:167], v[74:75], 1, v[36:37]
	global_load_dwordx4 v[194:197], v[166:167], off
	global_load_dwordx4 v[198:201], v[166:167], off offset:1024
	v_add_u32_e32 v74, 0x3400, v69
	v_lshl_add_u64 v[166:167], v[74:75], 1, v[36:37]
	global_load_dwordx4 v[202:205], v[166:167], off
	global_load_dwordx4 v[206:209], v[166:167], off offset:1024
	v_add_u32_e32 v74, 0x3800, v69
	v_lshl_add_u64 v[166:167], v[74:75], 1, v[36:37]
	global_load_dwordx4 v[210:213], v[166:167], off
	global_load_dwordx4 v[214:217], v[166:167], off offset:1024
	v_add_u32_e32 v74, 0x3c00, v69
	v_lshl_add_u64 v[166:167], v[74:75], 1, v[36:37]
	global_load_dwordx4 v[218:221], v[166:167], off
	global_load_dwordx4 v[230:233], v[166:167], off offset:1024
	s_and_saveexec_b64 s[4:5], vcc
	s_cbranch_execz .LBB0_287
	v_lshlrev_b32_e32 v168, 4, v68
	v_lshlrev_b64 v[32:33], 11, v[168:169]
	v_lshl_add_u64 v[32:33], v[36:37], 0, v[32:33]
	global_load_dwordx4 v[40:43], v[32:33], off offset:-3072
	global_load_dwordx4 v[44:47], v[32:33], off offset:-1024
	s_waitcnt vmcnt(1)
	v_lshlrev_b32_e32 v48, 16, v40
	v_and_b32_e32 v49, 0xffff0000, v40
	s_waitcnt vmcnt(0)
	v_lshlrev_b32_e32 v34, 16, v44
	v_and_b32_e32 v35, 0xffff0000, v44
	v_lshlrev_b32_e32 v50, 16, v41
	v_and_b32_e32 v51, 0xffff0000, v41
	v_lshlrev_b32_e32 v62, 16, v45
	v_and_b32_e32 v63, 0xffff0000, v45
	v_lshlrev_b32_e32 v32, 16, v42
	v_and_b32_e32 v33, 0xffff0000, v42
	v_lshlrev_b32_e32 v64, 16, v46
	v_and_b32_e32 v65, 0xffff0000, v46
	v_lshlrev_b32_e32 v52, 16, v43
	v_and_b32_e32 v53, 0xffff0000, v43
	v_lshlrev_b32_e32 v66, 16, v47
	v_and_b32_e32 v67, 0xffff0000, v47

; __device__ __forceinline__ float bf_lo(unsigned u) { return __uint_as_float(u << 16); }
; __device__ __forceinline__ float bf_hi(unsigned u) { return __uint_as_float(u & 0xffff0000u); }
; __device__ __forceinline__ void conv_phase(const bf16_t* proj, bf16_t* ycat, const float* cw, const float* cb, int tid) {
;     ...
;         for (int rr = 0; rr < 16; ++rr) {
;             const bf16_t* p = proj + (size_t)(row0 + rr) * 1024 + c0;
;             const u32x4 gb = *(const u32x4*)p, pc = *(const u32x4*)(p + 512);
;             float p0[8], y[8];
; #pragma unroll
;             for (int e = 0; e < 4; ++e) { p0[2 * e] = bf_lo(pc[e]); p0[2 * e + 1] = bf_hi(pc[e]); }
; #pragma unroll
;             for (int e = 0; e < 8; ++e) y[e] = w2[e] * p0[e] + w1[e] * p1[e] + w0[e] * p2[e] + bb[e];
;             u32x4 o;
; #pragma unroll
;             for (int e = 0; e < 4; ++e) o[e] = cvt_pk_bf16(bf_lo(gb[e]) * y[2 * e], bf_hi(gb[e]) * y[2 * e + 1]);
;             *(u32x4*)(ycat + (size_t)(row0 + rr) * DM + AW + c0) = o;
; #pragma unroll
;             for (int e = 0; e < 8; ++e) { p2[e] = p1[e]; p1[e] = p0[e]; }
;         }
.LBB0_288:
	v_add_u32_e32 v168, s4, v69
	v_lshlrev_b64 v[70:71], 1, v[168:169]
	v_lshl_add_u64 v[44:45], v[36:37], 0, v[70:71]
	s_waitcnt vmcnt(30)
	v_mov_b32_e32 v40, v76
	v_mov_b32_e32 v41, v77
	v_mov_b32_e32 v42, v78
	v_mov_b32_e32 v43, v79
	v_mov_b32_e32 v44, v80
	v_mov_b32_e32 v45, v81
	v_mov_b32_e32 v46, v82
	v_mov_b32_e32 v47, v83
	s_addk_i32 s4, 0x1000
	v_lshlrev_b32_e32 v60, 16, v44
	v_and_b32_e32 v61, 0xffff0000, v44
	v_pk_mul_f32 v[54:55], v[16:17], v[60:61]
	v_lshlrev_b32_e32 v58, 16, v45
	v_pk_fma_f32 v[54:55], v[12:13], v[34:35], v[54:55]
	v_and_b32_e32 v59, 0xffff0000, v45
	v_pk_fma_f32 v[48:49], v[4:5], v[48:49], v[54:55]
	v_pk_mul_f32 v[44:45], v[18:19], v[58:59]
	v_pk_add_f32 v[48:49], v[28:29], v[48:49]
	v_lshlrev_b32_e32 v54, 16, v40
	v_and_b32_e32 v55, 0xffff0000, v40
	v_pk_fma_f32 v[44:45], v[14:15], v[62:63], v[44:45]
	v_pk_mul_f32 v[48:49], v[48:49], v[54:55]
	v_pk_fma_f32 v[44:45], v[6:7], v[50:51], v[44:45]
	v_cvt_pk_bf16_f32 v40, v48, v49
	v_pk_add_f32 v[44:45], v[30:31], v[44:45]
	v_lshlrev_b32_e32 v48, 16, v41
	v_and_b32_e32 v49, 0xffff0000, v41
	v_pk_mul_f32 v[44:45], v[44:45], v[48:49]
	v_lshlrev_b32_e32 v56, 16, v46
	v_and_b32_e32 v57, 0xffff0000, v46
	v_cvt_pk_bf16_f32 v41, v44, v45
	v_pk_mul_f32 v[44:45], v[20:21], v[56:57]
	v_lshlrev_b32_e32 v54, 16, v47
	v_pk_fma_f32 v[44:45], v[8:9], v[64:65], v[44:45]
	v_and_b32_e32 v55, 0xffff0000, v47
	v_pk_fma_f32 v[32:33], v[0:1], v[32:33], v[44:45]
	v_lshlrev_b32_e32 v44, 16, v42
	v_pk_add_f32 v[32:33], v[24:25], v[32:33]
	v_and_b32_e32 v45, 0xffff0000, v42
	v_pk_mul_f32 v[32:33], v[32:33], v[44:45]
	v_lshlrev_b32_e32 v44, 16, v43
	v_cvt_pk_bf16_f32 v42, v32, v33
	v_pk_mul_f32 v[32:33], v[22:23], v[54:55]
	v_and_b32_e32 v45, 0xffff0000, v43
	v_pk_fma_f32 v[32:33], v[10:11], v[66:67], v[32:33]
	s_nop 0
	v_pk_fma_f32 v[32:33], v[2:3], v[52:53], v[32:33]
	s_nop 0
	v_pk_add_f32 v[32:33], v[26:27], v[32:33]
	s_nop 0
	v_pk_mul_f32 v[32:33], v[32:33], v[44:45]
	s_nop 0
	v_cvt_pk_bf16_f32 v43, v32, v33
	v_lshl_add_u64 v[32:33], v[38:39], 0, v[70:71]
	global_store_dwordx4 v[32:33], v[40:43], off offset:1024
	v_add_u32_e32 v32, 0x400, v168
	v_mov_b32_e32 v33, v169
	v_lshlrev_b64 v[52:53], 1, v[32:33]
	v_lshl_add_u64 v[32:33], v[36:37], 0, v[52:53]
	s_waitcnt vmcnt(29)
	v_mov_b32_e32 v48, v84
	v_mov_b32_e32 v49, v85
	v_mov_b32_e32 v50, v86
	v_mov_b32_e32 v51, v87
	v_mov_b32_e32 v70, v88
	v_mov_b32_e32 v71, v89
	v_mov_b32_e32 v72, v90
	v_mov_b32_e32 v73, v91
	v_lshlrev_b32_e32 v40, 16, v49
	v_lshlrev_b32_e32 v46, 16, v70
	v_and_b32_e32 v47, 0xffff0000, v70
	v_pk_mul_f32 v[32:33], v[16:17], v[46:47]
	v_lshlrev_b32_e32 v44, 16, v71
	v_pk_fma_f32 v[32:33], v[12:13], v[60:61], v[32:33]
	v_and_b32_e32 v45, 0xffff0000, v71
	v_pk_fma_f32 v[32:33], v[4:5], v[34:35], v[32:33]
	v_lshlrev_b32_e32 v34, 16, v48
	v_pk_add_f32 v[32:33], v[28:29], v[32:33]
	v_and_b32_e32 v35, 0xffff0000, v48
	v_pk_mul_f32 v[32:33], v[32:33], v[34:35]
	v_pk_mul_f32 v[34:35], v[18:19], v[44:45]
	v_and_b32_e32 v41, 0xffff0000, v49
	v_pk_fma_f32 v[34:35], v[14:15], v[58:59], v[34:35]
	v_lshlrev_b32_e32 v42, 16, v72
	v_pk_fma_f32 v[34:35], v[6:7], v[62:63], v[34:35]
	v_and_b32_e32 v43, 0xffff0000, v72
	v_pk_add_f32 v[34:35], v[30:31], v[34:35]
	v_cvt_pk_bf16_f32 v32, v32, v33
	v_pk_mul_f32 v[34:35], v[34:35], v[40:41]
	v_lshlrev_b32_e32 v40, 16, v50
	v_cvt_pk_bf16_f32 v33, v34, v35
	v_pk_mul_f32 v[34:35], v[20:21], v[42:43]
	v_and_b32_e32 v41, 0xffff0000, v50
	v_pk_fma_f32 v[34:35], v[8:9], v[56:57], v[34:35]
	v_lshlrev_b32_e32 v50, 16, v51
	v_pk_fma_f32 v[34:35], v[0:1], v[64:65], v[34:35]
	v_and_b32_e32 v51, 0xffff0000, v51
	v_pk_add_f32 v[34:35], v[24:25], v[34:35]
	s_nop 0
	v_pk_mul_f32 v[34:35], v[34:35], v[40:41]
	v_lshlrev_b32_e32 v40, 16, v73
	v_and_b32_e32 v41, 0xffff0000, v73
	v_pk_mul_f32 v[48:49], v[22:23], v[40:41]
	v_cvt_pk_bf16_f32 v34, v34, v35
	v_pk_fma_f32 v[48:49], v[10:11], v[54:55], v[48:49]
	s_nop 0
	v_pk_fma_f32 v[48:49], v[2:3], v[66:67], v[48:49]
	s_nop 0
	v_pk_add_f32 v[48:49], v[26:27], v[48:49]
	s_nop 0
	v_pk_mul_f32 v[48:49], v[48:49], v[50:51]
	s_nop 0
	v_cvt_pk_bf16_f32 v35, v48, v49
	v_lshl_add_u64 v[48:49], v[38:39], 0, v[52:53]
	global_store_dwordx4 v[48:49], v[32:35], off offset:1024
	s_nop 1
	v_add_u32_e32 v32, 0x800, v168
	v_mov_b32_e32 v33, v169
	v_lshlrev_b64 v[62:63], 1, v[32:33]
	v_lshl_add_u64 v[48:49], v[36:37], 0, v[62:63]
	s_waitcnt vmcnt(28)
	v_mov_b32_e32 v32, v92
	v_mov_b32_e32 v33, v93
	v_mov_b32_e32 v34, v94
	v_mov_b32_e32 v35, v95
	v_mov_b32_e32 v50, v96
	v_mov_b32_e32 v51, v97
	v_mov_b32_e32 v52, v98
	v_mov_b32_e32 v53, v99
	v_add_u32_e32 v168, 0xc00, v168
	v_lshlrev_b64 v[70:71], 1, v[168:169]
	v_lshlrev_b32_e32 v48, 16, v50
	v_and_b32_e32 v49, 0xffff0000, v50
	v_pk_mul_f32 v[64:65], v[16:17], v[48:49]
	v_lshlrev_b32_e32 v50, 16, v51
	v_pk_fma_f32 v[64:65], v[12:13], v[46:47], v[64:65]
	v_and_b32_e32 v51, 0xffff0000, v51
	v_pk_fma_f32 v[60:61], v[4:5], v[60:61], v[64:65]
	v_lshlrev_b32_e32 v64, 16, v32
	v_pk_add_f32 v[60:61], v[28:29], v[60:61]
	v_and_b32_e32 v65, 0xffff0000, v32
	v_pk_mul_f32 v[60:61], v[60:61], v[64:65]
	v_lshlrev_b32_e32 v32, 16, v33
	v_cvt_pk_bf16_f32 v64, v60, v61
	v_pk_mul_f32 v[60:61], v[18:19], v[50:51]
	v_and_b32_e32 v33, 0xffff0000, v33
	v_pk_fma_f32 v[60:61], v[14:15], v[44:45], v[60:61]
	s_nop 0
	v_pk_fma_f32 v[58:59], v[6:7], v[58:59], v[60:61]
	s_nop 0
	v_pk_add_f32 v[58:59], v[30:31], v[58:59]
	s_nop 0
	v_pk_mul_f32 v[32:33], v[58:59], v[32:33]
	s_nop 0
	v_cvt_pk_bf16_f32 v65, v32, v33
	v_lshlrev_b32_e32 v32, 16, v52
	v_and_b32_e32 v33, 0xffff0000, v52
	v_pk_mul_f32 v[58:59], v[20:21], v[32:33]
	v_lshlrev_b32_e32 v52, 16, v53
	v_pk_fma_f32 v[58:59], v[8:9], v[42:43], v[58:59]
	v_and_b32_e32 v53, 0xffff0000, v53
	v_pk_fma_f32 v[56:57], v[0:1], v[56:57], v[58:59]
	v_lshlrev_b32_e32 v58, 16, v34
	v_pk_add_f32 v[56:57], v[24:25], v[56:57]
	v_and_b32_e32 v59, 0xffff0000, v34
	v_pk_mul_f32 v[56:57], v[56:57], v[58:59]
	v_lshlrev_b32_e32 v34, 16, v35
	v_cvt_pk_bf16_f32 v66, v56, v57
	v_pk_mul_f32 v[56:57], v[22:23], v[52:53]
	v_and_b32_e32 v35, 0xffff0000, v35
	v_pk_fma_f32 v[56:57], v[10:11], v[40:41], v[56:57]
	s_nop 0
	v_pk_fma_f32 v[54:55], v[2:3], v[54:55], v[56:57]
	s_nop 0
	v_pk_add_f32 v[54:55], v[26:27], v[54:55]
	s_nop 0
	v_pk_mul_f32 v[34:35], v[54:55], v[34:35]
	s_nop 0
	v_cvt_pk_bf16_f32 v67, v34, v35
	v_lshl_add_u64 v[34:35], v[38:39], 0, v[62:63]
	global_store_dwordx4 v[34:35], v[64:67], off offset:1024
	v_lshl_add_u64 v[34:35], v[36:37], 0, v[70:71]
	s_waitcnt vmcnt(27)
; __device__ __forceinline__ float bf_lo(unsigned u) { return __uint_as_float(u << 16); }
; __device__ __forceinline__ float bf_hi(unsigned u) { return __uint_as_float(u & 0xffff0000u); }
; __device__ __forceinline__ void conv_phase(const bf16_t* proj, bf16_t* ycat, const float* cw, const float* cb, int tid) {
;     ...
;         for (int rr = 0; rr < 16; ++rr) {
;             const bf16_t* p = proj + (size_t)(row0 + rr) * 1024 + c0;
;             const u32x4 gb = *(const u32x4*)p, pc = *(const u32x4*)(p + 512);
;             float p0[8], y[8];
; #pragma unroll
;             for (int e = 0; e < 4; ++e) { p0[2 * e] = bf_lo(pc[e]); p0[2 * e + 1] = bf_hi(pc[e]); }
; #pragma unroll
;             for (int e = 0; e < 8; ++e) y[e] = w2[e] * p0[e] + w1[e] * p1[e] + w0[e] * p2[e] + bb[e];
;             u32x4 o;
; #pragma unroll
;             for (int e = 0; e < 4; ++e) o[e] = cvt_pk_bf16(bf_lo(gb[e]) * y[2 * e], bf_hi(gb[e]) * y[2 * e + 1]);
;             *(u32x4*)(ycat + (size_t)(row0 + rr) * DM + AW + c0) = o;
; #pragma unroll
;             for (int e = 0; e < 8; ++e) { p2[e] = p1[e]; p1[e] = p0[e]; }
;         }
	v_mov_b32_e32 v54, v100
	v_mov_b32_e32 v55, v101
	v_mov_b32_e32 v56, v102
	v_mov_b32_e32 v57, v103
	v_mov_b32_e32 v58, v104
	v_mov_b32_e32 v59, v105
	v_mov_b32_e32 v60, v106
	v_mov_b32_e32 v61, v107
	v_lshlrev_b32_e32 v34, 16, v58
	v_and_b32_e32 v35, 0xffff0000, v58
	v_pk_mul_f32 v[62:63], v[16:17], v[34:35]
	v_lshlrev_b32_e32 v64, 16, v60
	v_pk_fma_f32 v[62:63], v[12:13], v[48:49], v[62:63]
	v_and_b32_e32 v65, 0xffff0000, v60
	v_pk_fma_f32 v[46:47], v[4:5], v[46:47], v[62:63]
	v_lshlrev_b32_e32 v62, 16, v54
	v_pk_add_f32 v[46:47], v[28:29], v[46:47]
	v_and_b32_e32 v63, 0xffff0000, v54
	v_pk_mul_f32 v[46:47], v[46:47], v[62:63]
	v_lshlrev_b32_e32 v62, 16, v59
	v_and_b32_e32 v63, 0xffff0000, v59
	v_cvt_pk_bf16_f32 v54, v46, v47
	v_pk_mul_f32 v[46:47], v[18:19], v[62:63]
	v_lshlrev_b32_e32 v66, 16, v61
	v_pk_fma_f32 v[46:47], v[14:15], v[50:51], v[46:47]
	v_and_b32_e32 v67, 0xffff0000, v61
	v_pk_fma_f32 v[44:45], v[6:7], v[44:45], v[46:47]
	v_lshlrev_b32_e32 v46, 16, v55
	v_pk_add_f32 v[44:45], v[30:31], v[44:45]
	v_and_b32_e32 v47, 0xffff0000, v55
	v_pk_mul_f32 v[44:45], v[44:45], v[46:47]
	s_nop 0
	v_cvt_pk_bf16_f32 v55, v44, v45
	v_pk_mul_f32 v[44:45], v[20:21], v[64:65]
	s_nop 0
	v_pk_fma_f32 v[44:45], v[8:9], v[32:33], v[44:45]
	s_nop 0
	v_pk_fma_f32 v[42:43], v[0:1], v[42:43], v[44:45]
	v_lshlrev_b32_e32 v44, 16, v56
	v_pk_add_f32 v[42:43], v[24:25], v[42:43]
	v_and_b32_e32 v45, 0xffff0000, v56
	v_pk_mul_f32 v[42:43], v[42:43], v[44:45]
	s_nop 0
	v_cvt_pk_bf16_f32 v56, v42, v43
	v_pk_mul_f32 v[42:43], v[22:23], v[66:67]
	s_nop 0
	v_pk_fma_f32 v[42:43], v[10:11], v[52:53], v[42:43]
	s_nop 0
	v_pk_fma_f32 v[40:41], v[2:3], v[40:41], v[42:43]
	v_lshlrev_b32_e32 v42, 16, v57
	v_pk_add_f32 v[40:41], v[26:27], v[40:41]
	v_and_b32_e32 v43, 0xffff0000, v57
	v_pk_mul_f32 v[40:41], v[40:41], v[42:43]
	s_nop 0
	v_cvt_pk_bf16_f32 v57, v40, v41
	v_lshl_add_u64 v[40:41], v[38:39], 0, v[70:71]
	global_store_dwordx4 v[40:41], v[54:57], off offset:1024
	v_add_u32_e32 v168, s4, v69
	v_lshlrev_b64 v[70:71], 1, v[168:169]
	v_lshl_add_u64 v[44:45], v[36:37], 0, v[70:71]
	s_waitcnt vmcnt(26)
	v_mov_b32_e32 v40, v108
	v_mov_b32_e32 v41, v109
	v_mov_b32_e32 v42, v110
	v_mov_b32_e32 v43, v111
	v_mov_b32_e32 v44, v112
	v_mov_b32_e32 v45, v113
	v_mov_b32_e32 v46, v114
	v_mov_b32_e32 v47, v115
	s_addk_i32 s4, 0x1000
	v_lshlrev_b32_e32 v60, 16, v44
	v_and_b32_e32 v61, 0xffff0000, v44
	v_pk_mul_f32 v[54:55], v[16:17], v[60:61]
	v_lshlrev_b32_e32 v58, 16, v45
	v_pk_fma_f32 v[54:55], v[12:13], v[34:35], v[54:55]
	v_and_b32_e32 v59, 0xffff0000, v45
	v_pk_fma_f32 v[48:49], v[4:5], v[48:49], v[54:55]
	v_pk_mul_f32 v[44:45], v[18:19], v[58:59]
	v_pk_add_f32 v[48:49], v[28:29], v[48:49]
	v_lshlrev_b32_e32 v54, 16, v40
	v_and_b32_e32 v55, 0xffff0000, v40
	v_pk_fma_f32 v[44:45], v[14:15], v[62:63], v[44:45]
	v_pk_mul_f32 v[48:49], v[48:49], v[54:55]
	v_pk_fma_f32 v[44:45], v[6:7], v[50:51], v[44:45]
	v_cvt_pk_bf16_f32 v40, v48, v49
	v_pk_add_f32 v[44:45], v[30:31], v[44:45]
	v_lshlrev_b32_e32 v48, 16, v41
	v_and_b32_e32 v49, 0xffff0000, v41
	v_pk_mul_f32 v[44:45], v[44:45], v[48:49]
	v_lshlrev_b32_e32 v56, 16, v46
	v_and_b32_e32 v57, 0xffff0000, v46
	v_cvt_pk_bf16_f32 v41, v44, v45
	v_pk_mul_f32 v[44:45], v[20:21], v[56:57]
	v_lshlrev_b32_e32 v54, 16, v47
	v_pk_fma_f32 v[44:45], v[8:9], v[64:65], v[44:45]
	v_and_b32_e32 v55, 0xffff0000, v47
	v_pk_fma_f32 v[32:33], v[0:1], v[32:33], v[44:45]
	v_lshlrev_b32_e32 v44, 16, v42
	v_pk_add_f32 v[32:33], v[24:25], v[32:33]
	v_and_b32_e32 v45, 0xffff0000, v42
	v_pk_mul_f32 v[32:33], v[32:33], v[44:45]
	v_lshlrev_b32_e32 v44, 16, v43
	v_cvt_pk_bf16_f32 v42, v32, v33
	v_pk_mul_f32 v[32:33], v[22:23], v[54:55]
	v_and_b32_e32 v45, 0xffff0000, v43
	v_pk_fma_f32 v[32:33], v[10:11], v[66:67], v[32:33]
	s_nop 0
	v_pk_fma_f32 v[32:33], v[2:3], v[52:53], v[32:33]
	s_nop 0
	v_pk_add_f32 v[32:33], v[26:27], v[32:33]
	s_nop 0
	v_pk_mul_f32 v[32:33], v[32:33], v[44:45]
	s_nop 0
	v_cvt_pk_bf16_f32 v43, v32, v33
	v_lshl_add_u64 v[32:33], v[38:39], 0, v[70:71]
	global_store_dwordx4 v[32:33], v[40:43], off offset:1024
	v_add_u32_e32 v32, 0x400, v168
	v_mov_b32_e32 v33, v169
	v_lshlrev_b64 v[52:53], 1, v[32:33]
	v_lshl_add_u64 v[32:33], v[36:37], 0, v[52:53]
	s_waitcnt vmcnt(25)
	v_mov_b32_e32 v48, v116
	v_mov_b32_e32 v49, v117
	v_mov_b32_e32 v50, v118
	v_mov_b32_e32 v51, v119
	v_mov_b32_e32 v70, v120
	v_mov_b32_e32 v71, v121
	v_mov_b32_e32 v72, v122
	v_mov_b32_e32 v73, v123
	v_lshlrev_b32_e32 v40, 16, v49
	v_lshlrev_b32_e32 v46, 16, v70
	v_and_b32_e32 v47, 0xffff0000, v70
	v_pk_mul_f32 v[32:33], v[16:17], v[46:47]
	v_lshlrev_b32_e32 v44, 16, v71
	v_pk_fma_f32 v[32:33], v[12:13], v[60:61], v[32:33]
	v_and_b32_e32 v45, 0xffff0000, v71
	v_pk_fma_f32 v[32:33], v[4:5], v[34:35], v[32:33]
	v_lshlrev_b32_e32 v34, 16, v48
	v_pk_add_f32 v[32:33], v[28:29], v[32:33]
	v_and_b32_e32 v35, 0xffff0000, v48
	v_pk_mul_f32 v[32:33], v[32:33], v[34:35]
	v_pk_mul_f32 v[34:35], v[18:19], v[44:45]
	v_and_b32_e32 v41, 0xffff0000, v49
	v_pk_fma_f32 v[34:35], v[14:15], v[58:59], v[34:35]
	v_lshlrev_b32_e32 v42, 16, v72
	v_pk_fma_f32 v[34:35], v[6:7], v[62:63], v[34:35]
	v_and_b32_e32 v43, 0xffff0000, v72
	v_pk_add_f32 v[34:35], v[30:31], v[34:35]
	v_cvt_pk_bf16_f32 v32, v32, v33
	v_pk_mul_f32 v[34:35], v[34:35], v[40:41]
	v_lshlrev_b32_e32 v40, 16, v50
	v_cvt_pk_bf16_f32 v33, v34, v35
	v_pk_mul_f32 v[34:35], v[20:21], v[42:43]
	v_and_b32_e32 v41, 0xffff0000, v50
	v_pk_fma_f32 v[34:35], v[8:9], v[56:57], v[34:35]
	v_lshlrev_b32_e32 v50, 16, v51
	v_pk_fma_f32 v[34:35], v[0:1], v[64:65], v[34:35]
	v_and_b32_e32 v51, 0xffff0000, v51
	v_pk_add_f32 v[34:35], v[24:25], v[34:35]
	s_nop 0
	v_pk_mul_f32 v[34:35], v[34:35], v[40:41]
	v_lshlrev_b32_e32 v40, 16, v73
	v_and_b32_e32 v41, 0xffff0000, v73
	v_pk_mul_f32 v[48:49], v[22:23], v[40:41]
	v_cvt_pk_bf16_f32 v34, v34, v35
	v_pk_fma_f32 v[48:49], v[10:11], v[54:55], v[48:49]
	s_nop 0
	v_pk_fma_f32 v[48:49], v[2:3], v[66:67], v[48:49]
	s_nop 0
	v_pk_add_f32 v[48:49], v[26:27], v[48:49]
	s_nop 0
	v_pk_mul_f32 v[48:49], v[48:49], v[50:51]
	s_nop 0
	v_cvt_pk_bf16_f32 v35, v48, v49
	v_lshl_add_u64 v[48:49], v[38:39], 0, v[52:53]
	global_store_dwordx4 v[48:49], v[32:35], off offset:1024
	s_nop 1
	v_add_u32_e32 v32, 0x800, v168
	v_mov_b32_e32 v33, v169
	v_lshlrev_b64 v[62:63], 1, v[32:33]
	v_lshl_add_u64 v[48:49], v[36:37], 0, v[62:63]
	s_waitcnt vmcnt(24)
; __device__ __forceinline__ float bf_lo(unsigned u) { return __uint_as_float(u << 16); }
; __device__ __forceinline__ float bf_hi(unsigned u) { return __uint_as_float(u & 0xffff0000u); }
; __device__ __forceinline__ void conv_phase(const bf16_t* proj, bf16_t* ycat, const float* cw, const float* cb, int tid) {
;     ...
;         for (int rr = 0; rr < 16; ++rr) {
;             const bf16_t* p = proj + (size_t)(row0 + rr) * 1024 + c0;
;             const u32x4 gb = *(const u32x4*)p, pc = *(const u32x4*)(p + 512);
;             float p0[8], y[8];
; #pragma unroll
;             for (int e = 0; e < 4; ++e) { p0[2 * e] = bf_lo(pc[e]); p0[2 * e + 1] = bf_hi(pc[e]); }
; #pragma unroll
;             for (int e = 0; e < 8; ++e) y[e] = w2[e] * p0[e] + w1[e] * p1[e] + w0[e] * p2[e] + bb[e];
;             u32x4 o;
; #pragma unroll
;             for (int e = 0; e < 4; ++e) o[e] = cvt_pk_bf16(bf_lo(gb[e]) * y[2 * e], bf_hi(gb[e]) * y[2 * e + 1]);
;             *(u32x4*)(ycat + (size_t)(row0 + rr) * DM + AW + c0) = o;
; #pragma unroll
;             for (int e = 0; e < 8; ++e) { p2[e] = p1[e]; p1[e] = p0[e]; }
;         }
	v_mov_b32_e32 v32, v124
	v_mov_b32_e32 v33, v125
	v_mov_b32_e32 v34, v126
	v_mov_b32_e32 v35, v127
	v_mov_b32_e32 v50, v128
	v_mov_b32_e32 v51, v129
	v_mov_b32_e32 v52, v130
	v_mov_b32_e32 v53, v131
	v_add_u32_e32 v168, 0xc00, v168
	v_lshlrev_b64 v[70:71], 1, v[168:169]
	v_lshlrev_b32_e32 v48, 16, v50
	v_and_b32_e32 v49, 0xffff0000, v50
	v_pk_mul_f32 v[64:65], v[16:17], v[48:49]
	v_lshlrev_b32_e32 v50, 16, v51
	v_pk_fma_f32 v[64:65], v[12:13], v[46:47], v[64:65]
	v_and_b32_e32 v51, 0xffff0000, v51
	v_pk_fma_f32 v[60:61], v[4:5], v[60:61], v[64:65]
	v_lshlrev_b32_e32 v64, 16, v32
	v_pk_add_f32 v[60:61], v[28:29], v[60:61]
	v_and_b32_e32 v65, 0xffff0000, v32
	v_pk_mul_f32 v[60:61], v[60:61], v[64:65]
	v_lshlrev_b32_e32 v32, 16, v33
	v_cvt_pk_bf16_f32 v64, v60, v61
	v_pk_mul_f32 v[60:61], v[18:19], v[50:51]
	v_and_b32_e32 v33, 0xffff0000, v33
	v_pk_fma_f32 v[60:61], v[14:15], v[44:45], v[60:61]
	s_nop 0
	v_pk_fma_f32 v[58:59], v[6:7], v[58:59], v[60:61]
	s_nop 0
	v_pk_add_f32 v[58:59], v[30:31], v[58:59]
	s_nop 0
	v_pk_mul_f32 v[32:33], v[58:59], v[32:33]
	s_nop 0
	v_cvt_pk_bf16_f32 v65, v32, v33
	v_lshlrev_b32_e32 v32, 16, v52
	v_and_b32_e32 v33, 0xffff0000, v52
	v_pk_mul_f32 v[58:59], v[20:21], v[32:33]
	v_lshlrev_b32_e32 v52, 16, v53
	v_pk_fma_f32 v[58:59], v[8:9], v[42:43], v[58:59]
	v_and_b32_e32 v53, 0xffff0000, v53
	v_pk_fma_f32 v[56:57], v[0:1], v[56:57], v[58:59]
	v_lshlrev_b32_e32 v58, 16, v34
	v_pk_add_f32 v[56:57], v[24:25], v[56:57]
	v_and_b32_e32 v59, 0xffff0000, v34
	v_pk_mul_f32 v[56:57], v[56:57], v[58:59]
	v_lshlrev_b32_e32 v34, 16, v35
	v_cvt_pk_bf16_f32 v66, v56, v57
	v_pk_mul_f32 v[56:57], v[22:23], v[52:53]
	v_and_b32_e32 v35, 0xffff0000, v35
	v_pk_fma_f32 v[56:57], v[10:11], v[40:41], v[56:57]
	s_nop 0
	v_pk_fma_f32 v[54:55], v[2:3], v[54:55], v[56:57]
	s_nop 0
	v_pk_add_f32 v[54:55], v[26:27], v[54:55]
	s_nop 0
	v_pk_mul_f32 v[34:35], v[54:55], v[34:35]
	s_nop 0
	v_cvt_pk_bf16_f32 v67, v34, v35
	v_lshl_add_u64 v[34:35], v[38:39], 0, v[62:63]
	global_store_dwordx4 v[34:35], v[64:67], off offset:1024
	v_lshl_add_u64 v[34:35], v[36:37], 0, v[70:71]
	s_waitcnt vmcnt(23)
	v_mov_b32_e32 v54, v132
	v_mov_b32_e32 v55, v133
	v_mov_b32_e32 v56, v134
	v_mov_b32_e32 v57, v135
	v_mov_b32_e32 v58, v138
	v_mov_b32_e32 v59, v139
	v_mov_b32_e32 v60, v140
	v_mov_b32_e32 v61, v141
	v_lshlrev_b32_e32 v34, 16, v58
	v_and_b32_e32 v35, 0xffff0000, v58
	v_pk_mul_f32 v[62:63], v[16:17], v[34:35]
	v_lshlrev_b32_e32 v64, 16, v60
	v_pk_fma_f32 v[62:63], v[12:13], v[48:49], v[62:63]
	v_and_b32_e32 v65, 0xffff0000, v60
	v_pk_fma_f32 v[46:47], v[4:5], v[46:47], v[62:63]
	v_lshlrev_b32_e32 v62, 16, v54
	v_pk_add_f32 v[46:47], v[28:29], v[46:47]
	v_and_b32_e32 v63, 0xffff0000, v54
	v_pk_mul_f32 v[46:47], v[46:47], v[62:63]
	v_lshlrev_b32_e32 v62, 16, v59
	v_and_b32_e32 v63, 0xffff0000, v59
	v_cvt_pk_bf16_f32 v54, v46, v47
	v_pk_mul_f32 v[46:47], v[18:19], v[62:63]
	v_lshlrev_b32_e32 v66, 16, v61
	v_pk_fma_f32 v[46:47], v[14:15], v[50:51], v[46:47]
	v_and_b32_e32 v67, 0xffff0000, v61
	v_pk_fma_f32 v[44:45], v[6:7], v[44:45], v[46:47]
	v_lshlrev_b32_e32 v46, 16, v55
	v_pk_add_f32 v[44:45], v[30:31], v[44:45]
	v_and_b32_e32 v47, 0xffff0000, v55
	v_pk_mul_f32 v[44:45], v[44:45], v[46:47]
	s_nop 0
	v_cvt_pk_bf16_f32 v55, v44, v45
	v_pk_mul_f32 v[44:45], v[20:21], v[64:65]
	s_nop 0
	v_pk_fma_f32 v[44:45], v[8:9], v[32:33], v[44:45]
	s_nop 0
	v_pk_fma_f32 v[42:43], v[0:1], v[42:43], v[44:45]
	v_lshlrev_b32_e32 v44, 16, v56
	v_pk_add_f32 v[42:43], v[24:25], v[42:43]
	v_and_b32_e32 v45, 0xffff0000, v56
	v_pk_mul_f32 v[42:43], v[42:43], v[44:45]
	s_nop 0
	v_cvt_pk_bf16_f32 v56, v42, v43
	v_pk_mul_f32 v[42:43], v[22:23], v[66:67]
	s_nop 0
	v_pk_fma_f32 v[42:43], v[10:11], v[52:53], v[42:43]
	s_nop 0
	v_pk_fma_f32 v[40:41], v[2:3], v[40:41], v[42:43]
	v_lshlrev_b32_e32 v42, 16, v57
	v_pk_add_f32 v[40:41], v[26:27], v[40:41]
	v_and_b32_e32 v43, 0xffff0000, v57
	v_pk_mul_f32 v[40:41], v[40:41], v[42:43]
	s_nop 0
	v_cvt_pk_bf16_f32 v57, v40, v41
	v_lshl_add_u64 v[40:41], v[38:39], 0, v[70:71]
	global_store_dwordx4 v[40:41], v[54:57], off offset:1024
	v_add_u32_e32 v168, s4, v69
	v_lshlrev_b64 v[70:71], 1, v[168:169]
	v_lshl_add_u64 v[44:45], v[36:37], 0, v[70:71]
	s_waitcnt vmcnt(22)
	v_mov_b32_e32 v40, v142
	v_mov_b32_e32 v41, v143
	v_mov_b32_e32 v42, v144
	v_mov_b32_e32 v43, v145
	v_mov_b32_e32 v44, v146
	v_mov_b32_e32 v45, v147
	v_mov_b32_e32 v46, v148
	v_mov_b32_e32 v47, v149
	s_addk_i32 s4, 0x1000
	v_lshlrev_b32_e32 v60, 16, v44
	v_and_b32_e32 v61, 0xffff0000, v44
	v_pk_mul_f32 v[54:55], v[16:17], v[60:61]
	v_lshlrev_b32_e32 v58, 16, v45
	v_pk_fma_f32 v[54:55], v[12:13], v[34:35], v[54:55]
	v_and_b32_e32 v59, 0xffff0000, v45
	v_pk_fma_f32 v[48:49], v[4:5], v[48:49], v[54:55]
	v_pk_mul_f32 v[44:45], v[18:19], v[58:59]
	v_pk_add_f32 v[48:49], v[28:29], v[48:49]
	v_lshlrev_b32_e32 v54, 16, v40
	v_and_b32_e32 v55, 0xffff0000, v40
	v_pk_fma_f32 v[44:45], v[14:15], v[62:63], v[44:45]
	v_pk_mul_f32 v[48:49], v[48:49], v[54:55]
	v_pk_fma_f32 v[44:45], v[6:7], v[50:51], v[44:45]
	v_cvt_pk_bf16_f32 v40, v48, v49
	v_pk_add_f32 v[44:45], v[30:31], v[44:45]
	v_lshlrev_b32_e32 v48, 16, v41
	v_and_b32_e32 v49, 0xffff0000, v41
	v_pk_mul_f32 v[44:45], v[44:45], v[48:49]
	v_lshlrev_b32_e32 v56, 16, v46
	v_and_b32_e32 v57, 0xffff0000, v46
	v_cvt_pk_bf16_f32 v41, v44, v45
	v_pk_mul_f32 v[44:45], v[20:21], v[56:57]
	v_lshlrev_b32_e32 v54, 16, v47
	v_pk_fma_f32 v[44:45], v[8:9], v[64:65], v[44:45]
	v_and_b32_e32 v55, 0xffff0000, v47
	v_pk_fma_f32 v[32:33], v[0:1], v[32:33], v[44:45]
	v_lshlrev_b32_e32 v44, 16, v42
	v_pk_add_f32 v[32:33], v[24:25], v[32:33]
	v_and_b32_e32 v45, 0xffff0000, v42
	v_pk_mul_f32 v[32:33], v[32:33], v[44:45]
	v_lshlrev_b32_e32 v44, 16, v43
	v_cvt_pk_bf16_f32 v42, v32, v33
	v_pk_mul_f32 v[32:33], v[22:23], v[54:55]
	v_and_b32_e32 v45, 0xffff0000, v43
	v_pk_fma_f32 v[32:33], v[10:11], v[66:67], v[32:33]
	s_nop 0
	v_pk_fma_f32 v[32:33], v[2:3], v[52:53], v[32:33]
	s_nop 0
	v_pk_add_f32 v[32:33], v[26:27], v[32:33]
	s_nop 0
	v_pk_mul_f32 v[32:33], v[32:33], v[44:45]
	s_nop 0
	v_cvt_pk_bf16_f32 v43, v32, v33
	v_lshl_add_u64 v[32:33], v[38:39], 0, v[70:71]
	global_store_dwordx4 v[32:33], v[40:43], off offset:1024
	v_add_u32_e32 v32, 0x400, v168
	v_mov_b32_e32 v33, v169
	v_lshlrev_b64 v[52:53], 1, v[32:33]
	v_lshl_add_u64 v[32:33], v[36:37], 0, v[52:53]
	s_waitcnt vmcnt(21)
; __device__ __forceinline__ float bf_lo(unsigned u) { return __uint_as_float(u << 16); }
; __device__ __forceinline__ float bf_hi(unsigned u) { return __uint_as_float(u & 0xffff0000u); }
; __device__ __forceinline__ void conv_phase(const bf16_t* proj, bf16_t* ycat, const float* cw, const float* cb, int tid) {
;     ...
;         for (int rr = 0; rr < 16; ++rr) {
;             const bf16_t* p = proj + (size_t)(row0 + rr) * 1024 + c0;
;             const u32x4 gb = *(const u32x4*)p, pc = *(const u32x4*)(p + 512);
;             float p0[8], y[8];
; #pragma unroll
;             for (int e = 0; e < 4; ++e) { p0[2 * e] = bf_lo(pc[e]); p0[2 * e + 1] = bf_hi(pc[e]); }
; #pragma unroll
;             for (int e = 0; e < 8; ++e) y[e] = w2[e] * p0[e] + w1[e] * p1[e] + w0[e] * p2[e] + bb[e];
;             u32x4 o;
; #pragma unroll
;             for (int e = 0; e < 4; ++e) o[e] = cvt_pk_bf16(bf_lo(gb[e]) * y[2 * e], bf_hi(gb[e]) * y[2 * e + 1]);
;             *(u32x4*)(ycat + (size_t)(row0 + rr) * DM + AW + c0) = o;
; #pragma unroll
;             for (int e = 0; e < 8; ++e) { p2[e] = p1[e]; p1[e] = p0[e]; }
;         }
	v_mov_b32_e32 v48, v150
	v_mov_b32_e32 v49, v151
	v_mov_b32_e32 v50, v152
	v_mov_b32_e32 v51, v153
	v_mov_b32_e32 v70, v154
	v_mov_b32_e32 v71, v155
	v_mov_b32_e32 v72, v156
	v_mov_b32_e32 v73, v157
	v_lshlrev_b32_e32 v40, 16, v49
	v_lshlrev_b32_e32 v46, 16, v70
	v_and_b32_e32 v47, 0xffff0000, v70
	v_pk_mul_f32 v[32:33], v[16:17], v[46:47]
	v_lshlrev_b32_e32 v44, 16, v71
	v_pk_fma_f32 v[32:33], v[12:13], v[60:61], v[32:33]
	v_and_b32_e32 v45, 0xffff0000, v71
	v_pk_fma_f32 v[32:33], v[4:5], v[34:35], v[32:33]
	v_lshlrev_b32_e32 v34, 16, v48
	v_pk_add_f32 v[32:33], v[28:29], v[32:33]
	v_and_b32_e32 v35, 0xffff0000, v48
	v_pk_mul_f32 v[32:33], v[32:33], v[34:35]
	v_pk_mul_f32 v[34:35], v[18:19], v[44:45]
	v_and_b32_e32 v41, 0xffff0000, v49
	v_pk_fma_f32 v[34:35], v[14:15], v[58:59], v[34:35]
	v_lshlrev_b32_e32 v42, 16, v72
	v_pk_fma_f32 v[34:35], v[6:7], v[62:63], v[34:35]
	v_and_b32_e32 v43, 0xffff0000, v72
	v_pk_add_f32 v[34:35], v[30:31], v[34:35]
	v_cvt_pk_bf16_f32 v32, v32, v33
	v_pk_mul_f32 v[34:35], v[34:35], v[40:41]
	v_lshlrev_b32_e32 v40, 16, v50
	v_cvt_pk_bf16_f32 v33, v34, v35
	v_pk_mul_f32 v[34:35], v[20:21], v[42:43]
	v_and_b32_e32 v41, 0xffff0000, v50
	v_pk_fma_f32 v[34:35], v[8:9], v[56:57], v[34:35]
	v_lshlrev_b32_e32 v50, 16, v51
	v_pk_fma_f32 v[34:35], v[0:1], v[64:65], v[34:35]
	v_and_b32_e32 v51, 0xffff0000, v51
	v_pk_add_f32 v[34:35], v[24:25], v[34:35]
	s_nop 0
	v_pk_mul_f32 v[34:35], v[34:35], v[40:41]
	v_lshlrev_b32_e32 v40, 16, v73
	v_and_b32_e32 v41, 0xffff0000, v73
	v_pk_mul_f32 v[48:49], v[22:23], v[40:41]
	v_cvt_pk_bf16_f32 v34, v34, v35
	v_pk_fma_f32 v[48:49], v[10:11], v[54:55], v[48:49]
	s_nop 0
	v_pk_fma_f32 v[48:49], v[2:3], v[66:67], v[48:49]
	s_nop 0
	v_pk_add_f32 v[48:49], v[26:27], v[48:49]
	s_nop 0
	v_pk_mul_f32 v[48:49], v[48:49], v[50:51]
	s_nop 0
	v_cvt_pk_bf16_f32 v35, v48, v49
	v_lshl_add_u64 v[48:49], v[38:39], 0, v[52:53]
	global_store_dwordx4 v[48:49], v[32:35], off offset:1024
	s_nop 1
	v_add_u32_e32 v32, 0x800, v168
	v_mov_b32_e32 v33, v169
	v_lshlrev_b64 v[62:63], 1, v[32:33]
	v_lshl_add_u64 v[48:49], v[36:37], 0, v[62:63]
	s_waitcnt vmcnt(20)
	v_mov_b32_e32 v32, v158
	v_mov_b32_e32 v33, v159
	v_mov_b32_e32 v34, v160
	v_mov_b32_e32 v35, v161
	v_mov_b32_e32 v50, v162
	v_mov_b32_e32 v51, v163
	v_mov_b32_e32 v52, v164
	v_mov_b32_e32 v53, v165
	v_add_u32_e32 v168, 0xc00, v168
	v_lshlrev_b64 v[70:71], 1, v[168:169]
	v_lshlrev_b32_e32 v48, 16, v50
	v_and_b32_e32 v49, 0xffff0000, v50
	v_pk_mul_f32 v[64:65], v[16:17], v[48:49]
	v_lshlrev_b32_e32 v50, 16, v51
	v_pk_fma_f32 v[64:65], v[12:13], v[46:47], v[64:65]
	v_and_b32_e32 v51, 0xffff0000, v51
	v_pk_fma_f32 v[60:61], v[4:5], v[60:61], v[64:65]
	v_lshlrev_b32_e32 v64, 16, v32
	v_pk_add_f32 v[60:61], v[28:29], v[60:61]
	v_and_b32_e32 v65, 0xffff0000, v32
	v_pk_mul_f32 v[60:61], v[60:61], v[64:65]
	v_lshlrev_b32_e32 v32, 16, v33
	v_cvt_pk_bf16_f32 v64, v60, v61
	v_pk_mul_f32 v[60:61], v[18:19], v[50:51]
	v_and_b32_e32 v33, 0xffff0000, v33
	v_pk_fma_f32 v[60:61], v[14:15], v[44:45], v[60:61]
	s_nop 0
	v_pk_fma_f32 v[58:59], v[6:7], v[58:59], v[60:61]
	s_nop 0
	v_pk_add_f32 v[58:59], v[30:31], v[58:59]
	s_nop 0
	v_pk_mul_f32 v[32:33], v[58:59], v[32:33]
	s_nop 0
	v_cvt_pk_bf16_f32 v65, v32, v33
	v_lshlrev_b32_e32 v32, 16, v52
	v_and_b32_e32 v33, 0xffff0000, v52
	v_pk_mul_f32 v[58:59], v[20:21], v[32:33]
	v_lshlrev_b32_e32 v52, 16, v53
	v_pk_fma_f32 v[58:59], v[8:9], v[42:43], v[58:59]
	v_and_b32_e32 v53, 0xffff0000, v53
	v_pk_fma_f32 v[56:57], v[0:1], v[56:57], v[58:59]
	v_lshlrev_b32_e32 v58, 16, v34
	v_pk_add_f32 v[56:57], v[24:25], v[56:57]
	v_and_b32_e32 v59, 0xffff0000, v34
	v_pk_mul_f32 v[56:57], v[56:57], v[58:59]
	v_lshlrev_b32_e32 v34, 16, v35
	v_cvt_pk_bf16_f32 v66, v56, v57
	v_pk_mul_f32 v[56:57], v[22:23], v[52:53]
	v_and_b32_e32 v35, 0xffff0000, v35
	v_pk_fma_f32 v[56:57], v[10:11], v[40:41], v[56:57]
	s_nop 0
	v_pk_fma_f32 v[54:55], v[2:3], v[54:55], v[56:57]
	s_nop 0
	v_pk_add_f32 v[54:55], v[26:27], v[54:55]
	s_nop 0
	v_pk_mul_f32 v[34:35], v[54:55], v[34:35]
	s_nop 0
	v_cvt_pk_bf16_f32 v67, v34, v35
	v_lshl_add_u64 v[34:35], v[38:39], 0, v[62:63]
	global_store_dwordx4 v[34:35], v[64:67], off offset:1024
	v_lshl_add_u64 v[34:35], v[36:37], 0, v[70:71]
	s_waitcnt vmcnt(19)
	v_mov_b32_e32 v54, v186
	v_mov_b32_e32 v55, v187
	v_mov_b32_e32 v56, v188
	v_mov_b32_e32 v57, v189
	v_mov_b32_e32 v58, v190
	v_mov_b32_e32 v59, v191
	v_mov_b32_e32 v60, v192
	v_mov_b32_e32 v61, v193
	v_lshlrev_b32_e32 v34, 16, v58
	v_and_b32_e32 v35, 0xffff0000, v58
	v_pk_mul_f32 v[62:63], v[16:17], v[34:35]
	v_lshlrev_b32_e32 v64, 16, v60
	v_pk_fma_f32 v[62:63], v[12:13], v[48:49], v[62:63]
	v_and_b32_e32 v65, 0xffff0000, v60
	v_pk_fma_f32 v[46:47], v[4:5], v[46:47], v[62:63]
	v_lshlrev_b32_e32 v62, 16, v54
	v_pk_add_f32 v[46:47], v[28:29], v[46:47]
	v_and_b32_e32 v63, 0xffff0000, v54
	v_pk_mul_f32 v[46:47], v[46:47], v[62:63]
	v_lshlrev_b32_e32 v62, 16, v59
	v_and_b32_e32 v63, 0xffff0000, v59
	v_cvt_pk_bf16_f32 v54, v46, v47
	v_pk_mul_f32 v[46:47], v[18:19], v[62:63]
	v_lshlrev_b32_e32 v66, 16, v61
	v_pk_fma_f32 v[46:47], v[14:15], v[50:51], v[46:47]
	v_and_b32_e32 v67, 0xffff0000, v61
	v_pk_fma_f32 v[44:45], v[6:7], v[44:45], v[46:47]
	v_lshlrev_b32_e32 v46, 16, v55
	v_pk_add_f32 v[44:45], v[30:31], v[44:45]
	v_and_b32_e32 v47, 0xffff0000, v55
	v_pk_mul_f32 v[44:45], v[44:45], v[46:47]
	s_nop 0
	v_cvt_pk_bf16_f32 v55, v44, v45
	v_pk_mul_f32 v[44:45], v[20:21], v[64:65]
	s_nop 0
	v_pk_fma_f32 v[44:45], v[8:9], v[32:33], v[44:45]
	s_nop 0
	v_pk_fma_f32 v[42:43], v[0:1], v[42:43], v[44:45]
	v_lshlrev_b32_e32 v44, 16, v56
	v_pk_add_f32 v[42:43], v[24:25], v[42:43]
	v_and_b32_e32 v45, 0xffff0000, v56
	v_pk_mul_f32 v[42:43], v[42:43], v[44:45]
	s_nop 0
	v_cvt_pk_bf16_f32 v56, v42, v43
	v_pk_mul_f32 v[42:43], v[22:23], v[66:67]
	s_nop 0
	v_pk_fma_f32 v[42:43], v[10:11], v[52:53], v[42:43]
	s_nop 0
	v_pk_fma_f32 v[40:41], v[2:3], v[40:41], v[42:43]
	v_lshlrev_b32_e32 v42, 16, v57
	v_pk_add_f32 v[40:41], v[26:27], v[40:41]
	v_and_b32_e32 v43, 0xffff0000, v57
	v_pk_mul_f32 v[40:41], v[40:41], v[42:43]
	s_nop 0
	v_cvt_pk_bf16_f32 v57, v40, v41
	v_lshl_add_u64 v[40:41], v[38:39], 0, v[70:71]
	global_store_dwordx4 v[40:41], v[54:57], off offset:1024
	v_add_u32_e32 v168, s4, v69
	v_lshlrev_b64 v[70:71], 1, v[168:169]
	v_lshl_add_u64 v[44:45], v[36:37], 0, v[70:71]
	s_waitcnt vmcnt(18)
; __device__ __forceinline__ float bf_lo(unsigned u) { return __uint_as_float(u << 16); }
; __device__ __forceinline__ float bf_hi(unsigned u) { return __uint_as_float(u & 0xffff0000u); }
; __device__ __forceinline__ void conv_phase(const bf16_t* proj, bf16_t* ycat, const float* cw, const float* cb, int tid) {
;     ...
;         for (int rr = 0; rr < 16; ++rr) {
;             const bf16_t* p = proj + (size_t)(row0 + rr) * 1024 + c0;
;             const u32x4 gb = *(const u32x4*)p, pc = *(const u32x4*)(p + 512);
;             float p0[8], y[8];
; #pragma unroll
;             for (int e = 0; e < 4; ++e) { p0[2 * e] = bf_lo(pc[e]); p0[2 * e + 1] = bf_hi(pc[e]); }
; #pragma unroll
;             for (int e = 0; e < 8; ++e) y[e] = w2[e] * p0[e] + w1[e] * p1[e] + w0[e] * p2[e] + bb[e];
;             u32x4 o;
; #pragma unroll
;             for (int e = 0; e < 4; ++e) o[e] = cvt_pk_bf16(bf_lo(gb[e]) * y[2 * e], bf_hi(gb[e]) * y[2 * e + 1]);
;             *(u32x4*)(ycat + (size_t)(row0 + rr) * DM + AW + c0) = o;
; #pragma unroll
;             for (int e = 0; e < 8; ++e) { p2[e] = p1[e]; p1[e] = p0[e]; }
;         }
	v_mov_b32_e32 v40, v194
	v_mov_b32_e32 v41, v195
	v_mov_b32_e32 v42, v196
	v_mov_b32_e32 v43, v197
	v_mov_b32_e32 v44, v198
	v_mov_b32_e32 v45, v199
	v_mov_b32_e32 v46, v200
	v_mov_b32_e32 v47, v201
	s_addk_i32 s4, 0x1000
	v_lshlrev_b32_e32 v60, 16, v44
	v_and_b32_e32 v61, 0xffff0000, v44
	v_pk_mul_f32 v[54:55], v[16:17], v[60:61]
	v_lshlrev_b32_e32 v58, 16, v45
	v_pk_fma_f32 v[54:55], v[12:13], v[34:35], v[54:55]
	v_and_b32_e32 v59, 0xffff0000, v45
	v_pk_fma_f32 v[48:49], v[4:5], v[48:49], v[54:55]
	v_pk_mul_f32 v[44:45], v[18:19], v[58:59]
	v_pk_add_f32 v[48:49], v[28:29], v[48:49]
	v_lshlrev_b32_e32 v54, 16, v40
	v_and_b32_e32 v55, 0xffff0000, v40
	v_pk_fma_f32 v[44:45], v[14:15], v[62:63], v[44:45]
	v_pk_mul_f32 v[48:49], v[48:49], v[54:55]
	v_pk_fma_f32 v[44:45], v[6:7], v[50:51], v[44:45]
	v_cvt_pk_bf16_f32 v40, v48, v49
	v_pk_add_f32 v[44:45], v[30:31], v[44:45]
	v_lshlrev_b32_e32 v48, 16, v41
	v_and_b32_e32 v49, 0xffff0000, v41
	v_pk_mul_f32 v[44:45], v[44:45], v[48:49]
	v_lshlrev_b32_e32 v56, 16, v46
	v_and_b32_e32 v57, 0xffff0000, v46
	v_cvt_pk_bf16_f32 v41, v44, v45
	v_pk_mul_f32 v[44:45], v[20:21], v[56:57]
	v_lshlrev_b32_e32 v54, 16, v47
	v_pk_fma_f32 v[44:45], v[8:9], v[64:65], v[44:45]
	v_and_b32_e32 v55, 0xffff0000, v47
	v_pk_fma_f32 v[32:33], v[0:1], v[32:33], v[44:45]
	v_lshlrev_b32_e32 v44, 16, v42
	v_pk_add_f32 v[32:33], v[24:25], v[32:33]
	v_and_b32_e32 v45, 0xffff0000, v42
	v_pk_mul_f32 v[32:33], v[32:33], v[44:45]
	v_lshlrev_b32_e32 v44, 16, v43
	v_cvt_pk_bf16_f32 v42, v32, v33
	v_pk_mul_f32 v[32:33], v[22:23], v[54:55]
	v_and_b32_e32 v45, 0xffff0000, v43
	v_pk_fma_f32 v[32:33], v[10:11], v[66:67], v[32:33]
	s_nop 0
	v_pk_fma_f32 v[32:33], v[2:3], v[52:53], v[32:33]
	s_nop 0
	v_pk_add_f32 v[32:33], v[26:27], v[32:33]
	s_nop 0
	v_pk_mul_f32 v[32:33], v[32:33], v[44:45]
	s_nop 0
	v_cvt_pk_bf16_f32 v43, v32, v33
	v_lshl_add_u64 v[32:33], v[38:39], 0, v[70:71]
	global_store_dwordx4 v[32:33], v[40:43], off offset:1024
	v_add_u32_e32 v32, 0x400, v168
	v_mov_b32_e32 v33, v169
	v_lshlrev_b64 v[52:53], 1, v[32:33]
	v_lshl_add_u64 v[32:33], v[36:37], 0, v[52:53]
	s_waitcnt vmcnt(17)
	v_mov_b32_e32 v48, v202
	v_mov_b32_e32 v49, v203
	v_mov_b32_e32 v50, v204
	v_mov_b32_e32 v51, v205
	v_mov_b32_e32 v70, v206
	v_mov_b32_e32 v71, v207
	v_mov_b32_e32 v72, v208
	v_mov_b32_e32 v73, v209
	v_lshlrev_b32_e32 v40, 16, v49
	v_lshlrev_b32_e32 v46, 16, v70
	v_and_b32_e32 v47, 0xffff0000, v70
	v_pk_mul_f32 v[32:33], v[16:17], v[46:47]
	v_lshlrev_b32_e32 v44, 16, v71
	v_pk_fma_f32 v[32:33], v[12:13], v[60:61], v[32:33]
	v_and_b32_e32 v45, 0xffff0000, v71
	v_pk_fma_f32 v[32:33], v[4:5], v[34:35], v[32:33]
	v_lshlrev_b32_e32 v34, 16, v48
	v_pk_add_f32 v[32:33], v[28:29], v[32:33]
	v_and_b32_e32 v35, 0xffff0000, v48
	v_pk_mul_f32 v[32:33], v[32:33], v[34:35]
	v_pk_mul_f32 v[34:35], v[18:19], v[44:45]
	v_and_b32_e32 v41, 0xffff0000, v49
	v_pk_fma_f32 v[34:35], v[14:15], v[58:59], v[34:35]
	v_lshlrev_b32_e32 v42, 16, v72
	v_pk_fma_f32 v[34:35], v[6:7], v[62:63], v[34:35]
	v_and_b32_e32 v43, 0xffff0000, v72
	v_pk_add_f32 v[34:35], v[30:31], v[34:35]
	v_cvt_pk_bf16_f32 v32, v32, v33
	v_pk_mul_f32 v[34:35], v[34:35], v[40:41]
	v_lshlrev_b32_e32 v40, 16, v50
	v_cvt_pk_bf16_f32 v33, v34, v35
	v_pk_mul_f32 v[34:35], v[20:21], v[42:43]
	v_and_b32_e32 v41, 0xffff0000, v50
	v_pk_fma_f32 v[34:35], v[8:9], v[56:57], v[34:35]
	v_lshlrev_b32_e32 v50, 16, v51
	v_pk_fma_f32 v[34:35], v[0:1], v[64:65], v[34:35]
	v_and_b32_e32 v51, 0xffff0000, v51
	v_pk_add_f32 v[34:35], v[24:25], v[34:35]
	s_nop 0
	v_pk_mul_f32 v[34:35], v[34:35], v[40:41]
	v_lshlrev_b32_e32 v40, 16, v73
	v_and_b32_e32 v41, 0xffff0000, v73
	v_pk_mul_f32 v[48:49], v[22:23], v[40:41]
	v_cvt_pk_bf16_f32 v34, v34, v35
	v_pk_fma_f32 v[48:49], v[10:11], v[54:55], v[48:49]
	s_nop 0
	v_pk_fma_f32 v[48:49], v[2:3], v[66:67], v[48:49]
	s_nop 0
	v_pk_add_f32 v[48:49], v[26:27], v[48:49]
	s_nop 0
	v_pk_mul_f32 v[48:49], v[48:49], v[50:51]
	s_nop 0
	v_cvt_pk_bf16_f32 v35, v48, v49
	v_lshl_add_u64 v[48:49], v[38:39], 0, v[52:53]
	global_store_dwordx4 v[48:49], v[32:35], off offset:1024
	s_nop 1
	v_add_u32_e32 v32, 0x800, v168
	v_mov_b32_e32 v33, v169
	v_lshlrev_b64 v[62:63], 1, v[32:33]
	v_lshl_add_u64 v[48:49], v[36:37], 0, v[62:63]
	s_waitcnt vmcnt(16)
; __device__ __forceinline__ float bf_lo(unsigned u) { return __uint_as_float(u << 16); }
; __device__ __forceinline__ float bf_hi(unsigned u) { return __uint_as_float(u & 0xffff0000u); }
; __device__ __forceinline__ void conv_phase(const bf16_t* proj, bf16_t* ycat, const float* cw, const float* cb, int tid) {
;     ...
;     for (int chunk = (blockIdx.x * NTHR + tid) >> 6; chunk < M / 16; chunk += (gridDim.x * NTHR) >> 6) {
;     ...
;         for (int rr = 0; rr < 16; ++rr) {
;             const bf16_t* p = proj + (size_t)(row0 + rr) * 1024 + c0;
;             const u32x4 gb = *(const u32x4*)p, pc = *(const u32x4*)(p + 512);
;             float p0[8], y[8];
; #pragma unroll
;             for (int e = 0; e < 4; ++e) { p0[2 * e] = bf_lo(pc[e]); p0[2 * e + 1] = bf_hi(pc[e]); }
; #pragma unroll
;             for (int e = 0; e < 8; ++e) y[e] = w2[e] * p0[e] + w1[e] * p1[e] + w0[e] * p2[e] + bb[e];
;             u32x4 o;
; #pragma unroll
;             for (int e = 0; e < 4; ++e) o[e] = cvt_pk_bf16(bf_lo(gb[e]) * y[2 * e], bf_hi(gb[e]) * y[2 * e + 1]);
;             *(u32x4*)(ycat + (size_t)(row0 + rr) * DM + AW + c0) = o;
; #pragma unroll
;             for (int e = 0; e < 8; ++e) { p2[e] = p1[e]; p1[e] = p0[e]; }
;         }
	v_mov_b32_e32 v32, v210
	v_mov_b32_e32 v33, v211
	v_mov_b32_e32 v34, v212
	v_mov_b32_e32 v35, v213
	v_mov_b32_e32 v50, v214
	v_mov_b32_e32 v51, v215
	v_mov_b32_e32 v52, v216
	v_mov_b32_e32 v53, v217
	v_add_u32_e32 v168, 0xc00, v168
	v_lshlrev_b64 v[70:71], 1, v[168:169]
	v_lshlrev_b32_e32 v48, 16, v50
	v_and_b32_e32 v49, 0xffff0000, v50
	v_pk_mul_f32 v[64:65], v[16:17], v[48:49]
	v_lshlrev_b32_e32 v50, 16, v51
	v_pk_fma_f32 v[64:65], v[12:13], v[46:47], v[64:65]
	v_and_b32_e32 v51, 0xffff0000, v51
	v_pk_fma_f32 v[60:61], v[4:5], v[60:61], v[64:65]
	v_lshlrev_b32_e32 v64, 16, v32
	v_pk_add_f32 v[60:61], v[28:29], v[60:61]
	v_and_b32_e32 v65, 0xffff0000, v32
	v_pk_mul_f32 v[60:61], v[60:61], v[64:65]
	v_lshlrev_b32_e32 v32, 16, v33
	v_cvt_pk_bf16_f32 v64, v60, v61
	v_pk_mul_f32 v[60:61], v[18:19], v[50:51]
	v_and_b32_e32 v33, 0xffff0000, v33
	v_pk_fma_f32 v[60:61], v[14:15], v[44:45], v[60:61]
	s_nop 0
	v_pk_fma_f32 v[58:59], v[6:7], v[58:59], v[60:61]
	s_nop 0
	v_pk_add_f32 v[58:59], v[30:31], v[58:59]
	s_nop 0
	v_pk_mul_f32 v[32:33], v[58:59], v[32:33]
	s_nop 0
	v_cvt_pk_bf16_f32 v65, v32, v33
	v_lshlrev_b32_e32 v32, 16, v52
	v_and_b32_e32 v33, 0xffff0000, v52
	v_pk_mul_f32 v[58:59], v[20:21], v[32:33]
	v_lshlrev_b32_e32 v52, 16, v53
	v_pk_fma_f32 v[58:59], v[8:9], v[42:43], v[58:59]
	v_and_b32_e32 v53, 0xffff0000, v53
	v_pk_fma_f32 v[56:57], v[0:1], v[56:57], v[58:59]
	v_lshlrev_b32_e32 v58, 16, v34
	v_pk_add_f32 v[56:57], v[24:25], v[56:57]
	v_and_b32_e32 v59, 0xffff0000, v34
	v_pk_mul_f32 v[56:57], v[56:57], v[58:59]
	v_lshlrev_b32_e32 v34, 16, v35
	v_cvt_pk_bf16_f32 v66, v56, v57
	v_pk_mul_f32 v[56:57], v[22:23], v[52:53]
	v_and_b32_e32 v35, 0xffff0000, v35
	v_pk_fma_f32 v[56:57], v[10:11], v[40:41], v[56:57]
	s_nop 0
	v_pk_fma_f32 v[54:55], v[2:3], v[54:55], v[56:57]
	s_nop 0
	v_pk_add_f32 v[54:55], v[26:27], v[54:55]
	s_nop 0
	v_pk_mul_f32 v[34:35], v[54:55], v[34:35]
	s_nop 0
	v_cvt_pk_bf16_f32 v67, v34, v35
	v_lshl_add_u64 v[34:35], v[38:39], 0, v[62:63]
	global_store_dwordx4 v[34:35], v[64:67], off offset:1024
	v_lshl_add_u64 v[34:35], v[36:37], 0, v[70:71]
	s_waitcnt vmcnt(15)
	v_mov_b32_e32 v54, v218
	v_mov_b32_e32 v55, v219
	v_mov_b32_e32 v56, v220
	v_mov_b32_e32 v57, v221
	v_mov_b32_e32 v58, v230
	v_mov_b32_e32 v59, v231
	v_mov_b32_e32 v60, v232
	v_mov_b32_e32 v61, v233
	v_lshlrev_b32_e32 v34, 16, v58
	v_and_b32_e32 v35, 0xffff0000, v58
	v_pk_mul_f32 v[62:63], v[16:17], v[34:35]
	v_lshlrev_b32_e32 v64, 16, v60
	v_pk_fma_f32 v[62:63], v[12:13], v[48:49], v[62:63]
	v_and_b32_e32 v65, 0xffff0000, v60
	v_pk_fma_f32 v[46:47], v[4:5], v[46:47], v[62:63]
	v_lshlrev_b32_e32 v62, 16, v54
	v_pk_add_f32 v[46:47], v[28:29], v[46:47]
	v_and_b32_e32 v63, 0xffff0000, v54
	v_pk_mul_f32 v[46:47], v[46:47], v[62:63]
	v_lshlrev_b32_e32 v62, 16, v59
	v_and_b32_e32 v63, 0xffff0000, v59
	v_cvt_pk_bf16_f32 v54, v46, v47
	v_pk_mul_f32 v[46:47], v[18:19], v[62:63]
	v_lshlrev_b32_e32 v66, 16, v61
	v_pk_fma_f32 v[46:47], v[14:15], v[50:51], v[46:47]
	v_and_b32_e32 v67, 0xffff0000, v61
	v_pk_fma_f32 v[44:45], v[6:7], v[44:45], v[46:47]
	v_lshlrev_b32_e32 v46, 16, v55
	v_pk_add_f32 v[44:45], v[30:31], v[44:45]
	v_and_b32_e32 v47, 0xffff0000, v55
	v_pk_mul_f32 v[44:45], v[44:45], v[46:47]
	s_nop 0
	v_cvt_pk_bf16_f32 v55, v44, v45
	v_pk_mul_f32 v[44:45], v[20:21], v[64:65]
	s_nop 0
	v_pk_fma_f32 v[44:45], v[8:9], v[32:33], v[44:45]
	s_nop 0
	v_pk_fma_f32 v[42:43], v[0:1], v[42:43], v[44:45]
	v_lshlrev_b32_e32 v44, 16, v56
	v_pk_add_f32 v[42:43], v[24:25], v[42:43]
	v_and_b32_e32 v45, 0xffff0000, v56
	v_pk_mul_f32 v[42:43], v[42:43], v[44:45]
	s_nop 0
	v_cvt_pk_bf16_f32 v56, v42, v43
	v_pk_mul_f32 v[42:43], v[22:23], v[66:67]
	s_nop 0
	v_pk_fma_f32 v[42:43], v[10:11], v[52:53], v[42:43]
	s_nop 0
	v_pk_fma_f32 v[40:41], v[2:3], v[40:41], v[42:43]
	v_lshlrev_b32_e32 v42, 16, v57
	v_pk_add_f32 v[40:41], v[26:27], v[40:41]
	v_and_b32_e32 v43, 0xffff0000, v57
	v_pk_mul_f32 v[40:41], v[40:41], v[42:43]
	s_nop 0
	v_cvt_pk_bf16_f32 v57, v40, v41
	v_lshl_add_u64 v[40:41], v[38:39], 0, v[70:71]
	global_store_dwordx4 v[40:41], v[54:57], off offset:1024
	v_readlane_b32 s4, v252, 38
	s_nop 1
	v_add_u32_e32 v68, s4, v68
	s_movk_i32 s4, 0x7ff
	v_cmp_lt_u32_e32 vcc, s4, v68
	v_readlane_b32 s4, v251, 32
	s_or_b64 s[2:3], vcc, s[2:3]
	s_nop 0
	v_add_u32_e32 v69, s4, v69
	s_andn2_b64 exec, exec, s[2:3]
	s_cbranch_execnz .LBB0_285
